# T40: P2 order swap - light workgroups (no late in-proj unit, items < 608) run GLA pass 1 before their up-proj GEMM units
# baseline (speedup 1.0000x reference)
; #define FRESH() const int lane = fresh_lane(); int wave = wave_s; asm volatile("" : "+s"(wave)); const int tid = wave * 64 + lane; (void)tid; unsigned char* ws = p.ws; asm volatile("" : "+s"(ws)); (void)ws; Params pl = p; pl.ws = ws; (void)pl
; __global__ void __launch_bounds__(512, 2) hymba_fwd(Params p) {
;     ...
;         const bool bal = (G == 256);
;         const bool heavy = bal && !(vcu & 1);
;         const int hv = vcu >> 1;
;     ...
;         { FRESH();
;             pg8::Gemm g{(const bf16_t*)(ws + WS_CQ), (const bf16_t*)(ws + WS_WUP) + (size_t)l * WUP_ROWS * 256, 2 * T, WUP_ROWS, 256};
;             pg8::StaticOrder S;
;             if (!bal) S.init_up(vcu, G, 448); else if (heavy) S.init_up(hv, 448, 448); else S.init_up(128 + hv, 128, 448);
;             EpiUp E{(bf16_t*)(ws + WS_QR), (bf16_t*)(ws + WS_KVR)};
;             pg8::gemm_phase<EpiUp>(lds, g, S, E, tid);
;         }
;         __syncthreads();
;     ...
;         { FRESH();
;             int first, step, lim;
;             if (!bal) { first = vcu; step = G; lim = 1024; } else if (heavy) { first = 640 + hv * 3; step = 1; lim = first + 3; } else { first = hv * 5; step = 1; lim = first + 5; }
;             gla_pass<false>(p, l, lds, tid, lane, wave, first, step, lim); }
.LBB0_287:
	s_and_b32 s0, s91, 0x87
	s_cmpk_eq_u32 s0, 0x87
	s_cselect_b32 s1, 0, 1
	s_bfe_u32 s0, s91, 0x10003
	s_and_b32 s0, s0, s1
	s_nop 0
	v_writelane_b32 v255, s0, 63
	s_cbranch_scc1 .LBB0_304

; #define LAS __attribute__((address_space(3)))
; template <bool P3> DI void gla_load(const Params& p, int l, int item, int tid, int lane, int wave, GlaIn<P3>& g) {
;     const int c = item >> 2, h = item & 3, t0 = c * 64;
;     const bf16_t* Z = (const bf16_t*)(p.ws + WS_Z); const bf16_t* MISC = (const bf16_t*)(p.ws + WS_MISC);
; #pragma unroll
;     for (int e = 0; e < 2; ++e) g.vt[e] = *(const u32x4*)(Z + (size_t)(t0 + lane) * ZLD + Z_GV + h * 128 + (wave + 8 * e) * 8);
;     if constexpr (!P3) {
; #pragma unroll
;         for (int e = 0; e < 2; ++e) { const int i = tid + e * 512; g.lr[e] = MISC[(size_t)(t0 + (i >> 4)) * 256 + 192 + (i & 15)]; }
;     } else g.bc = *(const u32x4*)((const unsigned short*)(p.ws + WS_BC) + ((size_t)item * 64 + lane) * 64 + wave * 8);
; #pragma unroll
;     for (int jj = 0; jj < 8; ++jj) { const size_t ro = (size_t)(t0 + wave * 8 + jj) * ZLD + h * 64 + lane;
;         unsigned v = Z[ro + Z_GK]; if (P3) v |= (unsigned)Z[ro + Z_GQ] << 16; g.kq[jj] = v; }
;     if constexpr (!P3) {
;         const f32x4* wp = (const f32x4*)((const float*)(p.ws + WS_WGT) + ((size_t)l * 256 + h * 64 + lane) * 16);
; #pragma unroll
;         for (int q = 0; q < 4; ++q) g.wup[q] = wp[q];
;         g.bias = ((const float*)(p.ws + WS_SM))[l * 256 + h * 64 + lane];
;     }
; template <bool P3> DI void gla_pass(const Params& p, int l, LAS unsigned char* lds, int tid, int lane, int wave, int first, int step, int nitems) {
;     int it = first; if (it >= nitems) return;
;     GlaIn<P3> cur; gla_load<P3>(p, l, it & 1023, tid, lane, wave, cur);
;     for (;;) {
;         const int nx = it + step; const bool has = nx < nitems;
;         GlaIn<P3> nxt; gla_load<P3>(p, l, (has ? nx : it) & 1023, tid, lane, wave, nxt);
.LBB0_304:
	v_readlane_b32 s0, v255, 63
	s_nop 3
	s_cmp_eq_u32 s0, 2
	s_cbranch_scc1 .LBB0_312
	s_mov_b32 s2, s33
	s_mov_b64 s[0:1], s[50:51]
	s_waitcnt vmcnt(0) lgkmcnt(0)
	s_barrier
	v_mbcnt_lo_u32_b32 v42, -1, 0
	v_mbcnt_hi_u32_b32 v42, -1, v42
	s_nop 0
	v_readlane_b32 s0, v255, 17
	v_readlane_b32 s1, v255, 18
	s_andn2_b64 vcc, exec, s[0:1]
	s_cbranch_vccnz .LBB0_312
	v_readlane_b32 s3, v255, 19
	v_readlane_b32 s0, v255, 31
	v_readlane_b32 s1, v255, 32
	v_add_u32_e32 v2, s3, v42
	v_ashrrev_i32_e32 v3, 31, v2
	v_lshlrev_b64 v[2:3], 12, v[2:3]
	v_lshl_add_u64 v[2:3], s[0:1], 0, v[2:3]
	v_and_b32_e32 v27, 15, v42
	v_readlane_b32 s0, v254, 34
	s_lshl_b32 s26, s2, 3
	v_lshlrev_b32_e32 v0, 1, v27
	v_readlane_b32 s1, v254, 35
	v_ashrrev_i32_e32 v43, 31, v42
	v_readlane_b32 s4, v255, 21
	v_lshl_add_u64 v[44:45], s[0:1], 0, v[0:1]
	s_add_i32 s0, s3, s26
	v_lshlrev_b64 v[28:29], 1, v[42:43]
	v_readlane_b32 s5, v255, 22
	s_ashr_i32 s1, s0, 31
	v_lshl_add_u32 v26, s2, 6, v42
	v_lshl_add_u64 v[8:9], s[4:5], 0, v[28:29]
	s_lshl_b64 s[4:5], s[0:1], 12
	v_lshl_add_u64 v[10:11], v[8:9], 0, s[4:5]
	s_or_b32 s4, s0, 1
	s_ashr_i32 s5, s4, 31
	s_lshl_b64 s[4:5], s[4:5], 12
	v_lshl_add_u64 v[12:13], v[8:9], 0, s[4:5]
	s_or_b32 s4, s0, 2
	s_ashr_i32 s5, s4, 31
	s_lshl_b64 s[4:5], s[4:5], 12
	v_lshl_add_u64 v[14:15], v[8:9], 0, s[4:5]
	s_or_b32 s4, s0, 3
	s_ashr_i32 s5, s4, 31
	s_lshl_b64 s[4:5], s[4:5], 12
	v_lshl_add_u64 v[16:17], v[8:9], 0, s[4:5]
	s_or_b32 s4, s0, 4
	s_ashr_i32 s5, s4, 31
	s_lshl_b64 s[4:5], s[4:5], 12
	s_ashr_i32 s27, s26, 31
	v_lshl_add_u64 v[18:19], v[8:9], 0, s[4:5]
	s_or_b32 s4, s0, 5
	s_lshl_b64 s[22:23], s[26:27], 1
	v_ashrrev_i32_e32 v0, 4, v26
	v_add_u32_e32 v4, 0x200, v26
	s_ashr_i32 s5, s4, 31
	v_lshl_add_u64 v[6:7], v[2:3], 0, s[22:23]
	v_add_u32_e32 v2, s3, v0
	v_ashrrev_i32_e32 v54, 4, v4
	s_lshl_b64 s[4:5], s[4:5], 12
	v_ashrrev_i32_e32 v3, 31, v2
	v_add_u32_e32 v4, s3, v54
	v_lshl_add_u64 v[20:21], v[8:9], 0, s[4:5]
	s_or_b32 s4, s0, 6
	v_lshlrev_b64 v[2:3], 9, v[2:3]
	v_ashrrev_i32_e32 v5, 31, v4
	s_ashr_i32 s5, s4, 31
	v_lshl_add_u64 v[2:3], v[44:45], 0, v[2:3]
	v_lshlrev_b64 v[4:5], 9, v[4:5]
	s_lshl_b64 s[4:5], s[4:5], 12
	s_or_b32 s0, s0, 7
	v_lshl_add_u64 v[4:5], v[44:45], 0, v[4:5]
	global_load_ushort v60, v[2:3], off
	global_load_ushort v61, v[4:5], off
	global_load_ushort v32, v[10:11], off offset:512
	global_load_ushort v33, v[12:13], off offset:512
	global_load_ushort v34, v[14:15], off offset:512
	global_load_ushort v35, v[16:17], off offset:512
	global_load_ushort v36, v[18:19], off offset:512
	global_load_ushort v37, v[20:21], off offset:512
	v_lshl_add_u64 v[2:3], v[8:9], 0, s[4:5]
	s_ashr_i32 s1, s0, 31
	s_lshl_b32 s92, s86, 8
	v_readlane_b32 s4, v255, 40
	s_lshl_b64 s[0:1], s[0:1], 12
	v_lshl_add_u64 v[46:47], v[42:43], 0, s[92:93]
	v_readlane_b32 s5, v255, 41
	v_lshl_add_u64 v[4:5], v[8:9], 0, s[0:1]
	v_readlane_b32 s0, v254, 36
	v_lshl_add_u64 v[10:11], v[46:47], 0, s[4:5]
	v_lshlrev_b64 v[10:11], 6, v[10:11]
	v_readlane_b32 s1, v254, 37
	v_add_u32_e32 v55, s92, v42
	v_add_u32_e32 v24, s4, v55
	v_lshl_add_u64 v[22:23], s[0:1], 0, v[10:11]
	v_readlane_b32 s0, v254, 38
	global_load_ushort v38, v[2:3], off offset:512
	global_load_ushort v39, v[4:5], off offset:512
	s_nop 0
	global_load_dwordx4 v[2:5], v[6:7], off offset:1024
	s_nop 0
	global_load_dwordx4 v[6:9], v[6:7], off offset:1152
	s_nop 0
	global_load_dwordx4 v[10:13], v[22:23], off offset:32
	global_load_dwordx4 v[14:17], v[22:23], off offset:16
	global_load_dwordx4 v[18:21], v[22:23], off
	v_ashrrev_i32_e32 v25, 31, v24
	v_readlane_b32 s1, v254, 39
	s_lshl_b32 s3, s2, 9
	v_readlane_b32 s30, v254, 57
	v_lshl_add_u64 v[30:31], v[24:25], 2, s[0:1]
	global_load_dwordx4 v[22:25], v[22:23], off offset:48
	s_nop 0
	global_load_dword v69, v[30:31], off
	s_mul_i32 s0, s2, 0x500
	s_add_i32 s0, s0, 0
	v_lshl_add_u32 v56, v42, 1, s0
	v_readlane_b32 s0, v255, 47
	v_readlane_b32 s1, v255, 48
	v_lshlrev_b32_e32 v30, 2, v42
	v_lshl_add_u32 v57, v26, 2, s0
	s_lshl_b32 s0, s2, 8
	s_add_i32 s0, s1, s0
	s_cmp_gt_i32 s2, 0
	v_add_u32_e32 v58, s0, v30
	v_add_u32_e32 v59, s1, v30
	s_cselect_b64 s[0:1], -1, 0
	s_cmp_gt_i32 s2, 1
	s_cselect_b64 s[4:5], -1, 0
	s_cmp_gt_i32 s2, 2
	s_cselect_b64 s[6:7], -1, 0
	s_cmp_gt_i32 s2, 3
	s_cselect_b64 s[8:9], -1, 0
	s_cmp_gt_i32 s2, 4
	s_cselect_b64 s[10:11], -1, 0
	s_cmp_gt_i32 s2, 5
	s_cselect_b64 s[12:13], -1, 0
	s_cmp_gt_i32 s2, 6
	s_cselect_b64 s[14:15], -1, 0
	s_cmp_gt_i32 s2, 7
	v_lshlrev_b64 v[30:31], 7, v[42:43]
	v_lshrrev_b32_e32 v43, 2, v42
	s_cselect_b64 s[16:17], -1, 0
	s_lshl_b32 s20, s2, 4
	v_and_b32_e32 v43, 0xffffffc, v43
	s_cmp_eq_u32 s2, 0
	v_add_u32_e32 v43, s20, v43
	s_movk_i32 s2, 0x110
	v_mul_lo_u32 v66, v43, s2
	v_add_u32_e32 v43, 0x400, v26
	v_lshrrev_b32_e32 v43, 4, v43
	v_mul_lo_u32 v71, v43, s2
	v_add_u32_e32 v43, 0x600, v26
	v_readlane_b32 s31, v254, 58
	s_movk_i32 s18, 0xa0
	v_or_b32_e32 v41, s20, v27
	v_mul_u32_u24_e32 v63, 0xa0, v27
	v_lshl_add_u32 v65, v27, 2, 0
	v_lshlrev_b32_e32 v27, 4, v42
	v_lshrrev_b32_e32 v43, 4, v43
	v_lshl_add_u64 v[48:49], s[60:61], 0, v[28:29]
	v_lshl_add_u64 v[28:29], s[30:31], 0, v[30:31]
	v_mul_lo_u32 v40, v42, s18
	v_and_b32_e32 v62, -16, v42
	v_mul_lo_u32 v41, v41, s18
	v_and_b32_e32 v27, 0xf0, v27
	v_mul_lo_u32 v67, v0, s2
	v_mul_lo_u32 v70, v54, s2
	v_mul_lo_u32 v72, v43, s2
	v_lshl_add_u64 v[50:51], v[28:29], 0, s[22:23]
	s_mov_b32 s2, 0x5040100
	v_readlane_b32 s22, v254, 63
	v_add_u32_e32 v40, 0, v40
	s_cselect_b64 s[28:29], -1, 0
	v_add_u32_e32 v41, 0, v41
	v_add_u32_e32 v64, 0, v62
	v_add_u32_e32 v68, 0, v27
	v_ashrrev_i32_e32 v27, 31, v26
	s_waitcnt vmcnt(9)
	v_perm_b32 v79, v37, v36, s2
	v_perm_b32 v80, v35, v34, s2
	v_perm_b32 v81, v33, v32, s2
	v_readlane_b32 s23, v255, 0
	v_cmp_eq_u32_e64 s[18:19], 0, v26
	v_add_u32_e32 v43, s20, v40
	s_waitcnt vmcnt(7)
	v_perm_b32 v78, v39, v38, s2
	s_add_i32 s2, s3, 0
	v_lshl_add_u64 v[52:53], v[26:27], 4, s[22:23]
	s_add_i32 s2, s2, 0x11800
	v_add_u32_e32 v62, v41, v62
	v_add_u32_e32 v63, v64, v63
	v_add_u32_e32 v64, v65, v66
	v_add_u32_e32 v65, v68, v67
	v_add_u32_e32 v66, v68, v70
	v_add_u32_e32 v67, v68, v71
	v_add_u32_e32 v68, v68, v72
	v_readlane_b32 s3, v255, 20
	s_branch .LBB0_307

; #define FRESH() const int lane = fresh_lane(); int wave = wave_s; asm volatile("" : "+s"(wave)); const int tid = wave * 64 + lane; (void)tid; unsigned char* ws = p.ws; asm volatile("" : "+s"(ws)); (void)ws; Params pl = p; pl.ws = ws; (void)pl
; __global__ void __launch_bounds__(512, 2) hymba_fwd(Params p) {
;     ...
;         const bool bal = (G == 256);
;         const bool heavy = bal && !(vcu & 1);
;         const int hv = vcu >> 1;
;     ...
;         { FRESH();
;             pg8::Gemm g{(const bf16_t*)(ws + WS_CQ), (const bf16_t*)(ws + WS_WUP) + (size_t)l * WUP_ROWS * 256, 2 * T, WUP_ROWS, 256};
;             pg8::StaticOrder S;
;             if (!bal) S.init_up(vcu, G, 448); else if (heavy) S.init_up(hv, 448, 448); else S.init_up(128 + hv, 128, 448);
;             EpiUp E{(bf16_t*)(ws + WS_QR), (bf16_t*)(ws + WS_KVR)};
;             pg8::gemm_phase<EpiUp>(lds, g, S, E, tid);
;         }
;         __syncthreads();
;     ...
;         { FRESH();
;             int first, step, lim;
;             if (!bal) { first = vcu; step = G; lim = 1024; } else if (heavy) { first = 640 + hv * 3; step = 1; lim = first + 3; } else { first = hv * 5; step = 1; lim = first + 5; }
;             gla_pass<false>(p, l, lds, tid, lane, wave, first, step, lim); }
.LBB0_312:
	v_readlane_b32 s0, v255, 63
	s_nop 3
	s_cmp_lg_u32 s0, 1
	s_cbranch_scc1 .Lp2_end
	s_mov_b32 s0, 2
	s_nop 0
	v_writelane_b32 v255, s0, 63
	s_waitcnt vmcnt(0) lgkmcnt(0)
	s_barrier
	s_branch .Lp2_u
